# wi with P0 row split 10/22
# baseline (speedup 1.0000x reference)
.LBB0_152:
.LBB0_153:
	s_and_b64 s[8:9], s[8:9], exec
	s_cselect_b32 s14, 10, 22
.LBB0_154:
	s_andn2_b64 vcc, exec, s[10:11]
	s_mov_b32 s8, s39
	s_cbranch_vccnz .LBB0_160
	s_and_b64 vcc, exec, s[6:7]
	s_cbranch_vccz .LBB0_157
	s_add_i32 s6, s63, s3
	s_add_i32 s8, s6, 0x2400
	s_cbranch_execz .LBB0_158
	s_branch .LBB0_159
